# RNN tile loop instruction diet: scalar-base global addressing, persistent LDS addresses, interleaved gate epilogue without redundant max, DPP-modified scan ops; GEMM epilogue no-op adds removed
# speedup vs baseline: 1.0161x; 1.0091x over previous
.LBB0_53:
	v_lshl_add_u32 v146, s7, 8, v142
	v_lshl_or_b32 v140, s6, 8, v144
	v_ashrrev_i32_e32 v141, 31, v140
	v_ashrrev_i32_e32 v147, 31, v146
	v_lshl_add_u64 v[148:149], v[140:141], 1, s[12:13]
	v_lshlrev_b64 v[140:141], 11, v[146:147]
	v_lshl_add_u64 v[140:141], v[148:149], 0, v[140:141]
	v_add_f32_e32 v147, 0, v124
	v_add_f32_e32 v124, 0, v122
	v_cvt_pk_bf16_f32 v122, v126, v127
	v_add_f32_e32 v150, 0, v123
	v_cvt_pk_bf16_f32 v123, v128, v129
	v_cvt_pk_bf16_f32 v124, v124, v150
	v_cvt_pk_bf16_f32 v125, v147, v125
	global_store_dwordx4 v[140:141], v[122:125], off
	s_nop 1
	v_add_f32_e32 v122, 0, v108
	v_add_f32_e32 v108, 0, v106
	v_cvt_pk_bf16_f32 v106, v114, v115
	v_add_f32_e32 v123, 0, v107
	v_cvt_pk_bf16_f32 v107, v116, v117
	v_cvt_pk_bf16_f32 v108, v108, v123
	v_cvt_pk_bf16_f32 v109, v122, v109
	global_store_dwordx4 v[140:141], v[106:109], off offset:256
	s_nop 1
	v_or_b32_e32 v106, 16, v146
	v_ashrrev_i32_e32 v107, 31, v106
	v_lshlrev_b64 v[106:107], 11, v[106:107]
	v_lshl_add_u64 v[114:115], v[148:149], 0, v[106:107]
	v_add_f32_e32 v106, 0, v118
	v_add_f32_e32 v107, 0, v120
	v_add_f32_e32 v108, 0, v121
	v_add_f32_e32 v109, 0, v119
	v_cvt_pk_bf16_f32 v106, v106, v109
	v_cvt_pk_bf16_f32 v107, v107, v108
	v_cvt_pk_bf16_f32 v108, v110, v111
	v_cvt_pk_bf16_f32 v109, v112, v113
	global_store_dwordx4 v[114:115], v[106:109], off
	s_nop 1
	v_add_f32_e32 v106, 0, v92
	v_add_f32_e32 v92, 0, v90
	v_cvt_pk_bf16_f32 v90, v98, v99
	v_add_f32_e32 v107, 0, v91
	v_cvt_pk_bf16_f32 v91, v100, v101
	v_cvt_pk_bf16_f32 v92, v92, v107
	v_cvt_pk_bf16_f32 v93, v106, v93
	global_store_dwordx4 v[114:115], v[90:93], off offset:256
	s_nop 1
	v_or_b32_e32 v90, 32, v146
	v_ashrrev_i32_e32 v91, 31, v90
	v_lshlrev_b64 v[90:91], 11, v[90:91]
	v_lshl_add_u64 v[98:99], v[148:149], 0, v[90:91]
	v_add_f32_e32 v90, 0, v102
	v_add_f32_e32 v91, 0, v104
	v_add_f32_e32 v92, 0, v105
	v_add_f32_e32 v93, 0, v103
	v_cvt_pk_bf16_f32 v90, v90, v93
	v_cvt_pk_bf16_f32 v91, v91, v92
	v_cvt_pk_bf16_f32 v92, v94, v95
	v_cvt_pk_bf16_f32 v93, v96, v97
	global_store_dwordx4 v[98:99], v[90:93], off
	s_nop 1
	v_add_f32_e32 v90, 0, v76
	v_add_f32_e32 v76, 0, v74
	v_cvt_pk_bf16_f32 v74, v82, v83
	v_add_f32_e32 v91, 0, v75
	v_cvt_pk_bf16_f32 v75, v84, v85
	v_cvt_pk_bf16_f32 v76, v76, v91
	v_cvt_pk_bf16_f32 v77, v90, v77
	global_store_dwordx4 v[98:99], v[74:77], off offset:256
	s_nop 1
	v_or_b32_e32 v74, 48, v146
	v_ashrrev_i32_e32 v75, 31, v74
	v_lshlrev_b64 v[74:75], 11, v[74:75]
	v_lshl_add_u64 v[82:83], v[148:149], 0, v[74:75]
	v_add_f32_e32 v74, 0, v86
	v_add_f32_e32 v75, 0, v88
	v_add_f32_e32 v76, 0, v89
	v_add_f32_e32 v77, 0, v87
	v_cvt_pk_bf16_f32 v74, v74, v77
	v_cvt_pk_bf16_f32 v75, v75, v76
	v_cvt_pk_bf16_f32 v76, v78, v79
	v_cvt_pk_bf16_f32 v77, v80, v81
	global_store_dwordx4 v[82:83], v[74:77], off
	s_nop 1
	v_add_f32_e32 v74, 0, v68
	v_add_f32_e32 v68, 0, v66
	v_add_f32_e32 v75, 0, v67
	v_cvt_pk_bf16_f32 v66, v70, v71
	v_cvt_pk_bf16_f32 v67, v72, v73
	v_cvt_pk_bf16_f32 v68, v68, v75
	s_mov_b32 s6, 0x40000
	v_cvt_pk_bf16_f32 v69, v74, v69
	global_store_dwordx4 v[82:83], v[66:69], off offset:256
	s_nop 1
	v_add_f32_e32 v68, 0, v60
	v_add_f32_e32 v60, 0, v58
	v_cvt_pk_bf16_f32 v58, v62, v63
	v_add_co_u32_e32 v62, vcc, s6, v140
	s_nop 0
	v_addc_co_u32_e32 v63, vcc, 0, v141, vcc
	v_add_f32_e32 v69, 0, v59
	v_cvt_pk_bf16_f32 v59, v64, v65
	v_cvt_pk_bf16_f32 v60, v60, v69
	v_cvt_pk_bf16_f32 v61, v68, v61
	global_store_dwordx4 v[62:63], v[58:61], off
	s_nop 1
	v_lshl_add_u64 v[66:67], v[140:141], 0, s[36:37]
	v_add_f32_e32 v58, 0, v44
	v_add_f32_e32 v44, 0, v42
	v_add_f32_e32 v59, 0, v43
	v_cvt_pk_bf16_f32 v42, v50, v51
	v_cvt_pk_bf16_f32 v43, v52, v53
	v_cvt_pk_bf16_f32 v44, v44, v59
	s_mov_b64 s[6:7], 0x48000
	v_cvt_pk_bf16_f32 v45, v58, v45
	global_store_dwordx4 v[66:67], v[42:45], off offset:256
	s_nop 1
	v_lshl_add_u64 v[50:51], v[140:141], 0, s[6:7]
	v_add_f32_e32 v43, 0, v56
	v_add_f32_e32 v44, 0, v57
	v_add_f32_e32 v42, 0, v54
	s_mov_b32 s6, 0x48000
	v_add_f32_e32 v45, 0, v55
	v_cvt_pk_bf16_f32 v42, v42, v45
	v_cvt_pk_bf16_f32 v43, v43, v44
	v_cvt_pk_bf16_f32 v44, v46, v47
	v_add_co_u32_e32 v46, vcc, s6, v140
	s_nop 0
	v_addc_co_u32_e32 v47, vcc, 0, v141, vcc
	v_cvt_pk_bf16_f32 v45, v48, v49
	global_store_dwordx4 v[46:47], v[42:45], off
	s_nop 1
	v_add_f32_e32 v42, 0, v28
	v_add_f32_e32 v28, 0, v26
	v_add_f32_e32 v43, 0, v27
	v_cvt_pk_bf16_f32 v26, v34, v35
	v_cvt_pk_bf16_f32 v27, v36, v37
	v_cvt_pk_bf16_f32 v28, v28, v43
	s_mov_b64 s[6:7], 0x50000
	v_cvt_pk_bf16_f32 v29, v42, v29
	global_store_dwordx4 v[50:51], v[26:29], off offset:256
	s_nop 1
	v_lshl_add_u64 v[34:35], v[140:141], 0, s[6:7]
	v_add_f32_e32 v27, 0, v40
	v_add_f32_e32 v28, 0, v41
	v_add_f32_e32 v26, 0, v38
	s_mov_b32 s6, 0x50000
	v_add_f32_e32 v29, 0, v39
	v_cvt_pk_bf16_f32 v26, v26, v29
	v_cvt_pk_bf16_f32 v27, v27, v28
	v_cvt_pk_bf16_f32 v28, v30, v31
	v_add_co_u32_e32 v30, vcc, s6, v140
	s_nop 0
	v_addc_co_u32_e32 v31, vcc, 0, v141, vcc
	v_cvt_pk_bf16_f32 v29, v32, v33
	global_store_dwordx4 v[30:31], v[26:29], off
	s_nop 1
	v_add_f32_e32 v26, 0, v12
	v_add_f32_e32 v12, 0, v10
	v_add_f32_e32 v27, 0, v11
	v_cvt_pk_bf16_f32 v10, v18, v19
	v_cvt_pk_bf16_f32 v11, v20, v21
	v_cvt_pk_bf16_f32 v12, v12, v27
	s_mov_b64 s[6:7], 0x58000
	v_cvt_pk_bf16_f32 v13, v26, v13
	global_store_dwordx4 v[34:35], v[10:13], off offset:256
	s_nop 1
	v_lshl_add_u64 v[18:19], v[140:141], 0, s[6:7]
	v_add_f32_e32 v11, 0, v24
	v_add_f32_e32 v12, 0, v25
	v_add_f32_e32 v10, 0, v22
	s_mov_b32 s6, 0x58000
	v_add_f32_e32 v13, 0, v23
	v_cvt_pk_bf16_f32 v10, v10, v13
	v_cvt_pk_bf16_f32 v11, v11, v12
	v_cvt_pk_bf16_f32 v12, v14, v15
	v_add_co_u32_e32 v14, vcc, s6, v140
	s_nop 0
	v_addc_co_u32_e32 v15, vcc, 0, v141, vcc
	v_cvt_pk_bf16_f32 v13, v16, v17
	global_store_dwordx4 v[14:15], v[10:13], off
	s_nop 1
	s_andn2_b64 vcc, exec, s[38:39]
	v_add_f32_e32 v10, 0, v4
	v_add_f32_e32 v4, 0, v2
	s_mov_b64 s[10:11], -1
	v_add_f32_e32 v11, 0, v3
	v_cvt_pk_bf16_f32 v2, v6, v7
	v_cvt_pk_bf16_f32 v3, v8, v9
	v_cvt_pk_bf16_f32 v4, v4, v11
	v_cvt_pk_bf16_f32 v5, v10, v5
	global_store_dwordx4 v[18:19], v[2:5], off offset:256
	s_nop 1
	s_cbranch_vccnz .LBB0_42
	s_andn2_b64 vcc, exec, s[0:1]
	s_cbranch_vccnz .LBB0_41
	s_barrier
	s_branch .LBB0_41

.LBB0_76:
	s_ashr_i32 s10, s7, 31
	s_lshr_b32 s10, s10, 30
	s_lshl_b32 s21, s7, 8
	s_add_i32 s7, s7, s10
	s_ashr_i32 s10, s7, 2
	s_ashr_i32 s11, s10, 31
	s_lshl_b64 s[26:27], s[10:11], 26
	s_add_u32 s26, s12, s26
	s_addc_u32 s27, s13, s27
	s_lshl_b32 s7, s10, 10
	s_sub_i32 s7, s21, s7
	v_lshl_add_u32 v146, s6, 8, v142
	v_or_b32_e32 v140, s7, v144
	v_ashrrev_i32_e32 v141, 31, v140
	v_ashrrev_i32_e32 v147, 31, v146
	v_lshl_add_u64 v[148:149], v[140:141], 1, s[26:27]
	v_lshlrev_b64 v[140:141], 11, v[146:147]
	v_lshl_add_u64 v[140:141], v[148:149], 0, v[140:141]
	v_add_f32_e32 v147, 0, v124
	v_add_f32_e32 v124, 0, v122
	v_cvt_pk_bf16_f32 v122, v126, v127
	v_add_f32_e32 v150, 0, v123
	v_cvt_pk_bf16_f32 v123, v128, v129
	v_cvt_pk_bf16_f32 v124, v124, v150
	v_cvt_pk_bf16_f32 v125, v147, v125
	global_store_dwordx4 v[140:141], v[122:125], off
	s_nop 1
	v_add_f32_e32 v122, 0, v108
	v_add_f32_e32 v108, 0, v106
	v_cvt_pk_bf16_f32 v106, v114, v115
	v_add_f32_e32 v123, 0, v107
	v_cvt_pk_bf16_f32 v107, v116, v117
	v_cvt_pk_bf16_f32 v108, v108, v123
	v_cvt_pk_bf16_f32 v109, v122, v109
	global_store_dwordx4 v[140:141], v[106:109], off offset:256
	s_nop 1
	v_or_b32_e32 v106, 16, v146
	v_ashrrev_i32_e32 v107, 31, v106
	v_lshlrev_b64 v[106:107], 11, v[106:107]
	v_lshl_add_u64 v[114:115], v[148:149], 0, v[106:107]
	v_add_f32_e32 v106, 0, v118
	v_add_f32_e32 v107, 0, v120
	v_add_f32_e32 v108, 0, v121
	v_add_f32_e32 v109, 0, v119
	v_cvt_pk_bf16_f32 v106, v106, v109
	v_cvt_pk_bf16_f32 v107, v107, v108
	v_cvt_pk_bf16_f32 v108, v110, v111
	v_cvt_pk_bf16_f32 v109, v112, v113
	global_store_dwordx4 v[114:115], v[106:109], off
	s_nop 1
	v_add_f32_e32 v106, 0, v92
	v_add_f32_e32 v92, 0, v90
	v_cvt_pk_bf16_f32 v90, v98, v99
	v_add_f32_e32 v107, 0, v91
	v_cvt_pk_bf16_f32 v91, v100, v101
	v_cvt_pk_bf16_f32 v92, v92, v107
	v_cvt_pk_bf16_f32 v93, v106, v93
	global_store_dwordx4 v[114:115], v[90:93], off offset:256
	s_nop 1
	v_or_b32_e32 v90, 32, v146
	v_ashrrev_i32_e32 v91, 31, v90
	v_lshlrev_b64 v[90:91], 11, v[90:91]
	v_lshl_add_u64 v[98:99], v[148:149], 0, v[90:91]
	v_add_f32_e32 v90, 0, v102
	v_add_f32_e32 v91, 0, v104
	v_add_f32_e32 v92, 0, v105
	v_add_f32_e32 v93, 0, v103
	v_cvt_pk_bf16_f32 v90, v90, v93
	v_cvt_pk_bf16_f32 v91, v91, v92
	v_cvt_pk_bf16_f32 v92, v94, v95
	v_cvt_pk_bf16_f32 v93, v96, v97
	global_store_dwordx4 v[98:99], v[90:93], off
	s_nop 1
	v_add_f32_e32 v90, 0, v76
	v_add_f32_e32 v76, 0, v74
	v_cvt_pk_bf16_f32 v74, v82, v83
	v_add_f32_e32 v91, 0, v75
	v_cvt_pk_bf16_f32 v75, v84, v85
	v_cvt_pk_bf16_f32 v76, v76, v91
	v_cvt_pk_bf16_f32 v77, v90, v77
	global_store_dwordx4 v[98:99], v[74:77], off offset:256
	s_nop 1
	v_or_b32_e32 v74, 48, v146
	v_ashrrev_i32_e32 v75, 31, v74
	v_lshlrev_b64 v[74:75], 11, v[74:75]
	v_lshl_add_u64 v[82:83], v[148:149], 0, v[74:75]
	v_add_f32_e32 v74, 0, v86
	v_add_f32_e32 v75, 0, v88
	v_add_f32_e32 v76, 0, v89
	v_add_f32_e32 v77, 0, v87
	v_cvt_pk_bf16_f32 v74, v74, v77
	v_cvt_pk_bf16_f32 v75, v75, v76
	v_cvt_pk_bf16_f32 v76, v78, v79
	v_cvt_pk_bf16_f32 v77, v80, v81
	global_store_dwordx4 v[82:83], v[74:77], off
	s_nop 1
	v_add_f32_e32 v74, 0, v68
	v_add_f32_e32 v68, 0, v66
	v_add_f32_e32 v75, 0, v67
	v_cvt_pk_bf16_f32 v66, v70, v71
	v_cvt_pk_bf16_f32 v67, v72, v73
	v_cvt_pk_bf16_f32 v68, v68, v75
	s_mov_b32 s6, 0x40000
	v_cvt_pk_bf16_f32 v69, v74, v69
	global_store_dwordx4 v[82:83], v[66:69], off offset:256
	s_nop 1
	v_add_f32_e32 v68, 0, v60
	v_add_f32_e32 v60, 0, v58
	v_cvt_pk_bf16_f32 v58, v62, v63
	v_add_co_u32_e32 v62, vcc, s6, v140
	s_nop 0
	v_addc_co_u32_e32 v63, vcc, 0, v141, vcc
	v_add_f32_e32 v69, 0, v59
	v_cvt_pk_bf16_f32 v59, v64, v65
	v_cvt_pk_bf16_f32 v60, v60, v69
	v_cvt_pk_bf16_f32 v61, v68, v61
	global_store_dwordx4 v[62:63], v[58:61], off
	s_nop 1
	v_lshl_add_u64 v[66:67], v[140:141], 0, s[36:37]
	v_add_f32_e32 v58, 0, v44
	v_add_f32_e32 v44, 0, v42
	v_add_f32_e32 v59, 0, v43
	v_cvt_pk_bf16_f32 v42, v50, v51
	v_cvt_pk_bf16_f32 v43, v52, v53
	v_cvt_pk_bf16_f32 v44, v44, v59
	s_mov_b64 s[6:7], 0x48000
	v_cvt_pk_bf16_f32 v45, v58, v45
	global_store_dwordx4 v[66:67], v[42:45], off offset:256
	s_nop 1
	v_lshl_add_u64 v[50:51], v[140:141], 0, s[6:7]
	v_add_f32_e32 v43, 0, v56
	v_add_f32_e32 v44, 0, v57
	v_add_f32_e32 v42, 0, v54
	s_mov_b32 s6, 0x48000
	v_add_f32_e32 v45, 0, v55
	v_cvt_pk_bf16_f32 v42, v42, v45
	v_cvt_pk_bf16_f32 v43, v43, v44
	v_cvt_pk_bf16_f32 v44, v46, v47
	v_add_co_u32_e32 v46, vcc, s6, v140
	s_nop 0
	v_addc_co_u32_e32 v47, vcc, 0, v141, vcc
	v_cvt_pk_bf16_f32 v45, v48, v49
	global_store_dwordx4 v[46:47], v[42:45], off
	s_nop 1
	v_add_f32_e32 v42, 0, v28
	v_add_f32_e32 v28, 0, v26
	v_add_f32_e32 v43, 0, v27
	v_cvt_pk_bf16_f32 v26, v34, v35
	v_cvt_pk_bf16_f32 v27, v36, v37
	v_cvt_pk_bf16_f32 v28, v28, v43
	s_mov_b64 s[6:7], 0x50000
	v_cvt_pk_bf16_f32 v29, v42, v29
	global_store_dwordx4 v[50:51], v[26:29], off offset:256
	s_nop 1
	v_lshl_add_u64 v[34:35], v[140:141], 0, s[6:7]
	v_add_f32_e32 v27, 0, v40
	v_add_f32_e32 v28, 0, v41
	v_add_f32_e32 v26, 0, v38
	s_mov_b32 s6, 0x50000
	v_add_f32_e32 v29, 0, v39
	v_cvt_pk_bf16_f32 v26, v26, v29
	v_cvt_pk_bf16_f32 v27, v27, v28
	v_cvt_pk_bf16_f32 v28, v30, v31
	v_add_co_u32_e32 v30, vcc, s6, v140
	s_nop 0
	v_addc_co_u32_e32 v31, vcc, 0, v141, vcc
	v_cvt_pk_bf16_f32 v29, v32, v33
	global_store_dwordx4 v[30:31], v[26:29], off
	s_nop 1
	v_add_f32_e32 v26, 0, v12
	v_add_f32_e32 v12, 0, v10
	v_add_f32_e32 v27, 0, v11
	v_cvt_pk_bf16_f32 v10, v18, v19
	v_cvt_pk_bf16_f32 v11, v20, v21
	v_cvt_pk_bf16_f32 v12, v12, v27
	s_mov_b64 s[6:7], 0x58000
	v_cvt_pk_bf16_f32 v13, v26, v13
	global_store_dwordx4 v[34:35], v[10:13], off offset:256
	s_nop 1
	v_lshl_add_u64 v[18:19], v[140:141], 0, s[6:7]
	v_add_f32_e32 v11, 0, v24
	v_add_f32_e32 v12, 0, v25
	v_add_f32_e32 v10, 0, v22
	s_mov_b32 s6, 0x58000
	v_add_f32_e32 v13, 0, v23
	v_cvt_pk_bf16_f32 v10, v10, v13
	v_cvt_pk_bf16_f32 v11, v11, v12
	v_cvt_pk_bf16_f32 v12, v14, v15
	v_add_co_u32_e32 v14, vcc, s6, v140
	s_nop 0
	v_addc_co_u32_e32 v15, vcc, 0, v141, vcc
	v_cvt_pk_bf16_f32 v13, v16, v17
	global_store_dwordx4 v[14:15], v[10:13], off
	s_nop 1
	s_andn2_b64 vcc, exec, s[38:39]
	v_add_f32_e32 v10, 0, v4
	v_add_f32_e32 v4, 0, v2
	s_mov_b64 s[10:11], -1
	v_add_f32_e32 v11, 0, v3
	v_cvt_pk_bf16_f32 v2, v6, v7
	v_cvt_pk_bf16_f32 v3, v8, v9
	v_cvt_pk_bf16_f32 v4, v4, v11
	v_cvt_pk_bf16_f32 v5, v10, v5
	global_store_dwordx4 v[18:19], v[2:5], off offset:256
	s_nop 1
	s_cbranch_vccnz .LBB0_65
	s_andn2_b64 vcc, exec, s[0:1]
	s_cbranch_vccnz .LBB0_64
	s_barrier
	s_branch .LBB0_64

.LBB0_109:
	s_or_b64 exec, exec, s[10:11]
	s_lshl_b64 s[20:21], s[0:1], 12
	s_add_u32 s0, s16, s20
	s_addc_u32 s1, s17, s21
	s_add_u32 s0, s0, s6
	s_addc_u32 s1, s1, 0
	s_add_u32 s0, s0, s7
	v_ashrrev_i32_e32 v0, 6, v182
	s_addc_u32 s1, s1, 0
	v_mov_b32_e32 v171, v1
	v_lshlrev_b32_e32 v148, 1, v168
	v_lshl_or_b32 v142, v0, 2, v213
	v_lshl_add_u64 v[146:147], s[0:1], 0, v[170:171]
	v_lshl_add_u64 v[2:3], s[26:27], 0, v[170:171]
	v_add_u32_e32 v171, s52, v148
	v_lshlrev_b32_e32 v0, 4, v0
	s_movk_i32 s6, 0x420
	v_add3_u32 v143, v213, v141, v0
	v_or_b32_e32 v220, v0, v141
	v_lshl_add_u32 v224, v141, 6, s98
	v_mul_lo_u32 v225, v142, s6
	v_mul_lo_u32 v142, v142, s51
	v_lshlrev_b32_e32 v0, 4, v141
	v_mad_u32_u24 v141, v183, s51, v171
	v_mul_lo_u32 v150, v143, s51
	v_add_u32_e32 v226, s99, v142
	v_add_u32_e32 v227, s52, v142
	ds_read_u16 v142, v141
	ds_read_u16 v151, v141 offset:272
	ds_read_u16 v143, v141 offset:544
	ds_read_u16 v153, v141 offset:816
	ds_read_u16 v144, v141 offset:1088
	ds_read_u16 v155, v141 offset:1360
	ds_read_u16 v145, v141 offset:1632
	ds_read_u16 v141, v141 offset:1904
	v_lshlrev_b64 v[184:185], 12, v[168:169]
	v_mad_u32_u24 v152, v183, s51, v252
	s_waitcnt lgkmcnt(4)
	v_perm_b32 v143, v153, v143, s8
	s_waitcnt lgkmcnt(2)
	v_perm_b32 v144, v155, v144, s8
	s_waitcnt lgkmcnt(0)
	v_perm_b32 v145, v141, v145, s8
	v_mov_b32_e32 v141, s99
	v_mad_u32_u24 v141, v183, s51, v141
	v_perm_b32 v142, v151, v142, s8
	v_lshl_add_u64 v[146:147], v[146:147], 0, v[184:185]
	v_add_u32_e32 v175, v141, v148
	global_store_dwordx4 v[146:147], v[142:145], off
	ds_write_b16 v175, v120
	ds_write_b16_d16_hi v175, v120 offset:272
	v_add_u32_e32 v120, s99, v152
	v_add_u32_e32 v200, s99, v148
	v_mad_u32_u24 v154, v183, s51, v194
	v_add_u32_e32 v141, v200, v152
	v_add_u32_e32 v201, v120, v148
	v_mad_u32_u24 v156, v183, s51, v195
	ds_write_b16 v141, v121
	ds_write_b16_d16_hi v201, v121 offset:272
	v_add_u32_e32 v120, s99, v154
	v_add_u32_e32 v121, v200, v154
	ds_write_b16 v121, v122
	v_add_u32_e32 v202, v120, v148
	v_add_u32_e32 v120, s99, v156
	v_add_u32_e32 v121, v200, v156
	v_and_b32_e32 v149, 48, v182
	ds_write_b16 v121, v123
	v_add_u32_e32 v203, v120, v148
	v_lshlrev_b64 v[120:121], 11, v[168:169]
	v_lshl_add_u64 v[120:121], v[2:3], 0, v[120:121]
	s_mov_b32 s6, 0x40000
	v_add_u32_e32 v141, 0, v149
	ds_write_b16_d16_hi v202, v122 offset:272
	ds_write_b16_d16_hi v203, v123 offset:272
	v_add_co_u32_e32 v120, vcc, s6, v120
	v_add_u32_e32 v204, 0x19c00, v141
	s_nop 0
	v_addc_co_u32_e32 v121, vcc, 0, v121, vcc
	ds_read_b128 v[142:145], v204
	global_load_dwordx4 v[120:123], v[120:121], off
	v_add_u32_e32 v205, 0, v150
	ds_read_b128 v[146:149], v204 offset:64
	ds_read_b128 v[150:153], v205
	ds_read_b128 v[154:157], v205 offset:16
	ds_read_b128 v[158:161], v205 offset:32
	ds_read_b128 v[162:165], v205 offset:48
	s_waitcnt lgkmcnt(3)
	v_mfma_f32_16x16x32_bf16 v[142:145], v[4:7], v[150:153], v[142:145]
	s_cmp_eq_u32 s28, 0
	s_cselect_b64 vcc, -1, 0
	s_cmp_eq_u32 s28, 1
	s_waitcnt lgkmcnt(1)
	v_mfma_f32_16x16x32_bf16 v[146:149], v[12:15], v[158:161], v[146:149]
	s_cselect_b64 s[40:41], -1, 0
	s_cmp_eq_u32 s28, 2
	s_cselect_b64 s[42:43], -1, 0
	v_mfma_f32_16x16x32_bf16 v[142:145], v[8:11], v[154:157], v[142:145]
	s_cmp_eq_u32 s28, 3
	s_cselect_b64 s[44:45], -1, 0
	s_add_i32 s6, 0, 0x19800
	s_waitcnt lgkmcnt(0)
	v_mfma_f32_16x16x32_bf16 v[146:149], v[16:19], v[162:165], v[146:149]
	v_add_u32_e32 v224, v224, v225
	s_nop 1
	v_cvt_pk_bf16_f32 v142, v142, v143
	v_cvt_pk_bf16_f32 v143, v144, v145
	v_cndmask_b32_e32 v167, 0, v142, vcc
	v_cndmask_b32_e32 v190, 0, v143, vcc
	s_nop 0
	v_cvt_pk_bf16_f32 v144, v146, v147
	v_cvt_pk_bf16_f32 v145, v148, v149
	v_cndmask_b32_e32 v141, 0, v144, vcc
	v_cndmask_b32_e32 v166, 0, v145, vcc
	v_mfma_f32_16x16x32_bf16 v[146:149], v[52:55], v[142:145], 0
	v_add_u32_e32 v226, v226, v0
	v_add_u32_e32 v227, v227, v0
	v_mfma_f32_16x16x32_bf16 v[150:153], v[68:71], v[142:145], 0
	v_mfma_f32_16x16x32_bf16 v[154:157], v[84:87], v[142:145], 0
	v_mfma_f32_16x16x32_bf16 v[158:161], v[100:103], v[142:145], 0
	ds_read_b128 v[142:145], v204 offset:128
	ds_read_b128 v[162:165], v205 offset:64
	ds_read_b128 v[206:209], v205 offset:80
	ds_read_b128 v[228:231], v204 offset:192
	ds_read_b128 v[238:241], v205 offset:96
	ds_read_b128 v[242:245], v205 offset:112
	s_waitcnt lgkmcnt(4)
	v_mfma_f32_16x16x32_bf16 v[142:145], v[20:23], v[162:165], v[142:145]
	s_waitcnt lgkmcnt(1)
	v_mfma_f32_16x16x32_bf16 v[162:165], v[28:31], v[238:241], v[228:231]
	v_mfma_f32_16x16x32_bf16 v[142:145], v[24:27], v[206:209], v[142:145]
	s_waitcnt lgkmcnt(0)
	v_mfma_f32_16x16x32_bf16 v[162:165], v[32:35], v[242:245], v[162:165]
	s_nop 5
	v_cvt_pk_bf16_f32 v142, v142, v143
	v_cvt_pk_bf16_f32 v143, v144, v145
	v_cvt_pk_bf16_f32 v144, v162, v163
	v_cvt_pk_bf16_f32 v145, v164, v165
	v_cndmask_b32_e64 v166, v166, v145, s[40:41]
	v_cndmask_b32_e64 v141, v141, v144, s[40:41]
	v_mfma_f32_16x16x32_bf16 v[146:149], v[56:59], v[142:145], v[146:149]
	v_cndmask_b32_e64 v190, v190, v143, s[40:41]
	v_cndmask_b32_e64 v167, v167, v142, s[40:41]
	v_mfma_f32_16x16x32_bf16 v[150:153], v[72:75], v[142:145], v[150:153]
	v_mfma_f32_16x16x32_bf16 v[154:157], v[88:91], v[142:145], v[154:157]
	v_mfma_f32_16x16x32_bf16 v[158:161], v[104:107], v[142:145], v[158:161]
	ds_read_b128 v[142:145], v204 offset:256
	ds_read_b128 v[162:165], v205 offset:128
	ds_read_b128 v[206:209], v205 offset:144
	ds_read_b128 v[228:231], v204 offset:320
	ds_read_b128 v[238:241], v205 offset:160
	ds_read_b128 v[242:245], v205 offset:176
	s_waitcnt lgkmcnt(4)
	v_mfma_f32_16x16x32_bf16 v[142:145], v[36:39], v[162:165], v[142:145]
	s_waitcnt lgkmcnt(1)
	v_mfma_f32_16x16x32_bf16 v[162:165], v[44:47], v[238:241], v[228:231]
	v_mfma_f32_16x16x32_bf16 v[142:145], v[40:43], v[206:209], v[142:145]
	v_add_u32_e32 v206, 0x21a00, v140
	v_add_u32_e32 v207, 0x22200, v140
	s_waitcnt lgkmcnt(0)
	v_mfma_f32_16x16x32_bf16 v[162:165], v[48:51], v[242:245], v[162:165]
	s_nop 3
	v_cvt_pk_bf16_f32 v142, v142, v143
	v_cvt_pk_bf16_f32 v143, v144, v145
	s_nop 1
	v_cvt_pk_bf16_f32 v144, v162, v163
	v_cvt_pk_bf16_f32 v145, v164, v165
	v_cndmask_b32_e64 v141, v141, v144, s[42:43]
	v_cndmask_b32_e64 v166, v166, v145, s[42:43]
	v_mfma_f32_16x16x32_bf16 v[146:149], v[60:63], v[142:145], v[146:149]
	v_mfma_f32_16x16x32_bf16 v[162:165], v[76:79], v[142:145], v[150:153]
	v_mfma_f32_16x16x32_bf16 v[228:231], v[92:95], v[142:145], v[154:157]
	v_mfma_f32_16x16x32_bf16 v[156:159], v[108:111], v[142:145], v[158:161]
	s_nop 2
	v_cndmask_b32_e64 v160, v167, v142, s[42:43]
	v_cndmask_b32_e64 v161, v190, v143, s[42:43]
	ds_read_b128 v[142:145], v204 offset:384
	ds_read_b128 v[150:153], v205 offset:192
	ds_read_b128 v[238:241], v205 offset:208
	ds_read_b128 v[208:211], v204 offset:448
	ds_read_b128 v[242:245], v205 offset:224
	ds_read_b128 v[246:249], v205 offset:240
	ds_read_b128 v[190:193], v206
	s_waitcnt lgkmcnt(0)
	v_mfma_f32_16x16x32_bf16 v[142:145], v[190:193], v[150:153], v[142:145]
	ds_read_b128 v[150:153], v207
	s_waitcnt lgkmcnt(0)
	v_mfma_f32_16x16x32_bf16 v[150:153], v[150:153], v[242:245], v[208:211]
	s_nop 2
	v_add_u32_e32 v208, 0x21e00, v140
	ds_read_b128 v[190:193], v208
	v_add_u32_e32 v209, 0x22600, v140
	s_waitcnt lgkmcnt(0)
	v_mfma_f32_16x16x32_bf16 v[142:145], v[190:193], v[238:241], v[142:145]
	ds_read_b128 v[190:193], v209
	s_waitcnt lgkmcnt(0)
	v_mfma_f32_16x16x32_bf16 v[150:153], v[190:193], v[246:249], v[150:153]
	s_nop 4
	v_cvt_pk_bf16_f32 v190, v142, v143
	v_cvt_pk_bf16_f32 v191, v144, v145
	s_nop 0
	v_cvt_pk_bf16_f32 v192, v150, v151
	v_cvt_pk_bf16_f32 v193, v152, v153
	v_cndmask_b32_e64 v219, v141, v192, s[44:45]
	v_cndmask_b32_e64 v218, v166, v193, s[44:45]
	v_mfma_f32_16x16x32_bf16 v[140:143], v[112:115], v[190:193], v[156:159]
	s_nop 2
	v_cndmask_b32_e64 v156, v161, v191, s[44:45]
	v_lshlrev_b32_e32 v215, 16, v156
	v_and_b32_e32 v216, 0xffff0000, v156
	v_lshlrev_b32_e32 v156, 2, v217
	v_add_u32_e32 v210, s6, v156
	v_mfma_f32_16x16x32_bf16 v[152:155], v[64:67], v[190:193], v[146:149]
	v_add_u32_e32 v211, s53, v156
	v_cndmask_b32_e64 v157, v160, v190, s[44:45]
	v_add_u32_e32 v212, s54, v156
	v_mfma_f32_16x16x32_bf16 v[144:147], v[80:83], v[190:193], v[162:165]
	v_lshlrev_b32_e32 v221, 16, v157
	v_and_b32_e32 v214, 0xffff0000, v157
	ds_read_b128 v[156:159], v212
	ds_read_b128 v[164:167], v210
	ds_read_b128 v[160:163], v211
	v_mfma_f32_16x16x32_bf16 v[148:151], v[96:99], v[190:193], v[228:231]
	s_waitcnt lgkmcnt(1)
	v_add_f32_e32 v152, v152, v164
	v_exp_f32_e32 v152, v152
	v_and_b32_e32 v164, 0xffff0000, v219
	s_waitcnt lgkmcnt(0)
	s_nop 2
	v_add_f32_e32 v148, v148, v160
	v_exp_f32_e32 v148, v148
	v_add_f32_e32 v152, 1.0, v152
	v_rcp_f32_e64 v152, -v152
	v_add_f32_e32 v149, v149, v161
	v_add_f32_e32 v148, 1.0, v148
	v_rcp_f32_e32 v148, v148
	v_mul_f32_e32 v152, v156, v152
	v_exp_f32_e32 v190, v152
	v_exp_f32_e32 v149, v149
	v_mul_f32_e32 v148, v148, v221
	v_or_b32_e32 v161, 16, v217
	v_fma_f32 v152, -v190, v190, 1.0
	v_max_f32_e32 v152, 0, v152
	v_sqrt_f32_e32 v152, v152
	v_add_f32_e32 v149, 1.0, v149
	v_rcp_f32_e32 v149, v149
	v_mul_f32_e32 v191, v148, v152
	v_mul_u32_u24_e32 v148, 0x210, v213
	v_add_lshl_u32 v160, v220, v148, 3
	v_add_f32_e32 v148, v153, v165
	v_exp_f32_e32 v148, v148
	v_mul_f32_e32 v149, v149, v214
	v_add_u32_e32 v213, s98, v160
	ds_write_b64 v213, v[190:191]
	v_add_f32_e32 v148, 1.0, v148
	v_rcp_f32_e64 v148, -v148
	v_lshlrev_b32_e32 v165, 16, v218
	v_mul_f32_e32 v148, v157, v148
	v_exp_f32_e32 v148, v148
	s_nop 0
	v_fma_f32 v152, -v148, v148, 1.0
	v_max_f32_e32 v152, 0, v152
	v_sqrt_f32_e32 v152, v152
	s_nop 0
	v_mul_f32_e32 v149, v149, v152
	v_add_u32_e32 v152, 0x420, v160
	v_add_u32_e32 v214, s98, v152
	ds_write_b64 v214, v[148:149]
	v_add_f32_e32 v148, v154, v166
	v_exp_f32_e32 v148, v148
	v_add_f32_e32 v149, v150, v162
	v_exp_f32_e32 v149, v149
	v_and_b32_e32 v166, 0xffff0000, v218
	v_add_f32_e32 v148, 1.0, v148
	v_rcp_f32_e64 v148, -v148
	v_add_f32_e32 v149, 1.0, v149
	v_rcp_f32_e32 v149, v149
	v_mul_f32_e32 v148, v158, v148
	v_exp_f32_e32 v148, v148
	v_mul_f32_e32 v149, v149, v215
	v_fma_f32 v150, -v148, v148, 1.0
	v_max_f32_e32 v150, 0, v150
	v_sqrt_f32_e32 v150, v150
	s_nop 0
	v_mul_f32_e32 v149, v149, v150
	v_add_u32_e32 v150, 0x840, v160
	v_add_u32_e32 v215, s98, v150
	ds_write_b64 v215, v[148:149]
	v_add_f32_e32 v148, v155, v167
	v_exp_f32_e32 v148, v148
	v_add_f32_e32 v149, v151, v163
	v_exp_f32_e32 v149, v149
	v_lshlrev_b32_e32 v163, 16, v219
	v_add_f32_e32 v148, 1.0, v148
	v_rcp_f32_e64 v148, -v148
	v_add_f32_e32 v149, 1.0, v149
	v_rcp_f32_e32 v149, v149
	v_mul_f32_e32 v148, v159, v148
	v_exp_f32_e32 v148, v148
	v_mul_f32_e32 v149, v149, v216
	v_fma_f32 v150, -v148, v148, 1.0
	v_max_f32_e32 v150, 0, v150
	v_sqrt_f32_e32 v150, v150
	s_nop 0
	v_mul_f32_e32 v149, v149, v150
	v_add_u32_e32 v150, 0xc60, v160
	v_add_u32_e32 v216, s98, v150
	ds_write_b64 v216, v[148:149]
	v_lshlrev_b32_e32 v148, 2, v161
	v_add_u32_e32 v217, s6, v148
	ds_read_b128 v[156:159], v217
	v_add_u32_e32 v218, s53, v148
	ds_read_b128 v[152:155], v218
	v_add_u32_e32 v219, s54, v148
	ds_read_b128 v[148:151], v219
	s_waitcnt lgkmcnt(2)
	v_add_f32_e32 v144, v144, v156
	v_exp_f32_e32 v144, v144
	s_waitcnt lgkmcnt(1)
	v_add_f32_e32 v140, v140, v152
	v_exp_f32_e32 v140, v140
	v_add_f32_e32 v141, v141, v153
	v_add_f32_e32 v144, 1.0, v144
	v_rcp_f32_e64 v144, -v144
	v_add_f32_e32 v140, 1.0, v140
	v_rcp_f32_e32 v140, v140
	v_exp_f32_e32 v141, v141
	s_waitcnt lgkmcnt(0)
	v_mul_f32_e32 v144, v148, v144
	v_exp_f32_e32 v162, v144
	v_mul_f32_e32 v140, v140, v163
	v_add_f32_e32 v141, 1.0, v141
	v_rcp_f32_e32 v141, v141
	v_fma_f32 v144, -v162, v162, 1.0
	v_max_f32_e32 v144, 0, v144
	v_sqrt_f32_e32 v144, v144
	v_mul_f32_e32 v141, v141, v164
	v_mul_f32_e32 v163, v140, v144
	v_mul_u32_u24_e32 v140, 0x84, v161
	v_add_lshl_u32 v140, v140, v220, 3
	v_add_u32_e32 v220, s98, v140
	v_add_f32_e32 v140, v145, v157
	v_exp_f32_e32 v140, v140
	ds_write_b64 v220, v[162:163]
	v_mov_b32_e32 v161, v1
	v_add_f32_e32 v140, 1.0, v140
	v_rcp_f32_e64 v140, -v140
	s_nop 0
	v_mul_f32_e32 v140, v149, v140
	v_exp_f32_e32 v140, v140
	s_nop 0
	v_fma_f32 v144, -v140, v140, 1.0
	v_max_f32_e32 v144, 0, v144
	v_sqrt_f32_e32 v144, v144
	s_nop 0
	v_mul_f32_e32 v141, v141, v144
	v_add_u32_e32 v144, 0x4620, v160
	v_add_u32_e32 v221, s98, v144
	ds_write_b64 v221, v[140:141]
	v_add_f32_e32 v140, v146, v158
	v_exp_f32_e32 v140, v140
	v_add_f32_e32 v141, v142, v154
	v_exp_f32_e32 v141, v141
	v_add_f32_e32 v140, 1.0, v140
	v_rcp_f32_e64 v140, -v140
	v_add_f32_e32 v141, 1.0, v141
	v_rcp_f32_e32 v141, v141
	v_mul_f32_e32 v140, v150, v140
	v_exp_f32_e32 v140, v140
	v_mul_f32_e32 v141, v141, v165
	v_fma_f32 v142, -v140, v140, 1.0
	v_max_f32_e32 v142, 0, v142
	v_sqrt_f32_e32 v142, v142
	s_nop 0
	v_mul_f32_e32 v141, v141, v142
	v_add_u32_e32 v142, 0x4a40, v160
	v_add_u32_e32 v222, s98, v142
	ds_write_b64 v222, v[140:141]
	v_add_f32_e32 v140, v147, v159
	v_exp_f32_e32 v140, v140
	v_add_f32_e32 v141, v143, v155
	v_exp_f32_e32 v141, v141
	v_add_f32_e32 v140, 1.0, v140
	v_rcp_f32_e64 v140, -v140
	v_add_f32_e32 v141, 1.0, v141
	v_rcp_f32_e32 v141, v141
	v_mul_f32_e32 v140, v151, v140
	v_exp_f32_e32 v140, v140
	v_mul_f32_e32 v141, v141, v166
	v_fma_f32 v142, -v140, v140, 1.0
	v_max_f32_e32 v142, 0, v142
	v_sqrt_f32_e32 v142, v142
	s_nop 0
	v_mul_f32_e32 v141, v141, v142
	v_add_u32_e32 v142, 0x4e60, v160
	v_add_u32_e32 v223, s98, v142
	ds_write_b64 v223, v[140:141]
	s_waitcnt lgkmcnt(0)
	s_barrier
	ds_read_b128 v[148:151], v224
	ds_read_b128 v[152:155], v224 offset:16
	ds_read_b128 v[144:147], v224 offset:32
	ds_read_b128 v[140:143], v224 offset:48
	s_waitcnt lgkmcnt(3)
	v_fma_f32 v149, 0, v148, v149
	v_fma_f32 v156, v150, v149, v151
	v_mul_f32_e32 v157, v148, v150
	s_waitcnt lgkmcnt(2)
	v_fma_f32 v158, v152, v156, v153
	v_mul_f32_e32 v159, v157, v152
	v_mul_f32_e32 v160, v154, v159
	v_fmac_f32_e32 v155, v154, v158
	s_waitcnt lgkmcnt(1)
	v_fma_f32 v145, v144, v155, v145
	v_mul_f32_e32 v144, v144, v160
	v_mul_f32_e32 v154, v146, v144
	v_fmac_f32_e32 v147, v146, v145
	s_waitcnt lgkmcnt(0)
	v_fma_f32 v141, v140, v147, v141
	v_mul_f32_e32 v140, v140, v154
	v_mul_f32_e32 v146, v142, v140
	v_fmac_f32_e32 v143, v142, v141
	v_mov_b32_e32 v142, 1.0
	v_mov_b32_e32 v150, v1
	v_mov_b32_e32 v151, 1.0
	v_mov_b32_dpp v142, v146 row_shr:1 row_mask:0xf bank_mask:0xf
	v_mov_b32_dpp v150, v143 row_shr:1 row_mask:0xf bank_mask:0xf
	v_fma_f32 v150, v146, v150, v143
	v_mul_f32_e32 v142, v146, v142
	v_mov_b32_e32 v152, v1
	s_nop 0
	v_mov_b32_dpp v151, v142 row_shr:2 row_mask:0xf bank_mask:0xf
	v_mov_b32_dpp v152, v150 row_shr:2 row_mask:0xf bank_mask:0xf
	v_fmac_f32_e32 v150, v142, v152
	v_mul_f32_e32 v142, v142, v151
	v_mov_b32_e32 v151, 1.0
	v_mov_b32_e32 v152, v1
	s_nop 0
	v_mov_b32_dpp v151, v142 row_shr:4 row_mask:0xf bank_mask:0xf
	v_mov_b32_dpp v152, v150 row_shr:4 row_mask:0xf bank_mask:0xf
	v_fmac_f32_e32 v150, v142, v152
	v_mul_f32_e32 v142, v142, v151
	v_mov_b32_e32 v151, 1.0
	v_mov_b32_e32 v152, v1
	s_nop 0
	v_mov_b32_dpp v151, v142 row_shr:8 row_mask:0xf bank_mask:0xf
	v_mov_b32_dpp v152, v150 row_shr:8 row_mask:0xf bank_mask:0xf
	v_fmac_f32_e32 v150, v142, v152
	v_mul_f32_e32 v142, v142, v151
	v_mov_b32_e32 v151, 1.0
	v_mov_b32_dpp v161, v150 row_shr:1 row_mask:0xf bank_mask:0xf
	v_fmac_f32_e32 v150, 0, v142
	v_mov_b32_dpp v151, v142 row_shr:1 row_mask:0xf bank_mask:0xf
	v_fmac_f32_e32 v161, 0, v151
	ds_bpermute_b32 v225, v196, v150
	ds_read_b128 v[150:153], v226
	v_fmac_f32_e32 v145, v144, v161
	v_fmac_f32_e32 v149, v148, v161
	v_fmac_f32_e32 v147, v154, v161
	v_fmac_f32_e32 v141, v140, v161
	s_waitcnt lgkmcnt(0)
	v_lshlrev_b32_e32 v163, 16, v152
	v_lshlrev_b32_e32 v142, 16, v150
	v_mul_f32_e32 v144, v145, v163
	v_mul_f32_e32 v145, 0xbfb8aa3b, v163
	v_mul_f32_e32 v148, v149, v142
	v_mul_f32_e32 v142, 0xbfb8aa3b, v142
	v_exp_f32_e32 v145, v145
	v_exp_f32_e32 v142, v142
	v_and_b32_e32 v150, 0xffff0000, v150
	v_and_b32_e32 v152, 0xffff0000, v152
	v_add_f32_e32 v145, 1.0, v145
	v_add_f32_e32 v142, 1.0, v142
	v_rcp_f32_e32 v145, v145
	v_rcp_f32_e32 v142, v142
	v_lshlrev_b32_e32 v164, 16, v153
	v_lshlrev_b32_e32 v162, 16, v151
	v_fmac_f32_e32 v156, v157, v161
	v_mul_f32_e32 v149, 0xbfb8aa3b, v150
	v_mul_f32_e32 v144, v144, v145
	v_mul_f32_e32 v145, v147, v152
	v_mul_f32_e32 v147, 0xbfb8aa3b, v152
	v_mul_f32_e32 v140, v141, v164
	v_mul_f32_e32 v141, 0xbfb8aa3b, v164
	v_mul_f32_e32 v142, v148, v142
	v_mul_f32_e32 v148, v156, v150
	v_exp_f32_e32 v149, v149
	v_mul_f32_e32 v150, 0xbfb8aa3b, v162
	v_exp_f32_e32 v147, v147
	v_exp_f32_e32 v141, v141
	v_exp_f32_e32 v150, v150
	v_add_f32_e32 v149, 1.0, v149
	v_add_f32_e32 v147, 1.0, v147
	v_add_f32_e32 v141, 1.0, v141
	v_rcp_f32_e32 v149, v149
	v_add_f32_e32 v150, 1.0, v150
	v_rcp_f32_e32 v147, v147
	v_rcp_f32_e32 v141, v141
	v_rcp_f32_e32 v150, v150
	v_and_b32_e32 v153, 0xffff0000, v153
	v_fmac_f32_e32 v158, v159, v161
	v_and_b32_e32 v151, 0xffff0000, v151
	v_mul_f32_e32 v148, v148, v149
	v_mul_f32_e32 v149, v158, v162
	v_fmac_f32_e32 v155, v160, v161
	v_mul_f32_e32 v145, v145, v147
	v_mul_f32_e32 v147, v140, v141
	v_mul_f32_e32 v141, 0xbfb8aa3b, v153
	v_mul_f32_e32 v149, v149, v150
	v_mul_f32_e32 v150, v155, v151
	v_mul_f32_e32 v151, 0xbfb8aa3b, v151
	v_exp_f32_e32 v141, v141
	v_exp_f32_e32 v151, v151
	v_fmac_f32_e32 v143, v146, v161
	v_mul_f32_e32 v140, v143, v153
	v_add_f32_e32 v141, 1.0, v141
	v_add_f32_e32 v151, 1.0, v151
	v_rcp_f32_e32 v141, v141
	v_rcp_f32_e32 v151, v151
	v_mul_f32_e32 v143, v140, v141
	v_mul_f32_e32 v150, v150, v151
	v_cvt_pk_bf16_f32 v140, v142, v148
	v_cvt_pk_bf16_f32 v141, v149, v150
	v_cvt_pk_bf16_f32 v142, v144, v145
	v_cvt_pk_bf16_f32 v143, v147, v143
	ds_write_b128 v227, v[140:143]
	s_waitcnt vmcnt(5)
	ds_write_b128 v177, v[124:127] offset:816
	s_waitcnt vmcnt(4)
	ds_write_b128 v179, v[128:131] offset:816
	s_waitcnt vmcnt(3)
	ds_write_b128 v181, v[132:135] offset:816
	s_waitcnt vmcnt(2)
	ds_write_b128 v199, v[136:139] offset:816
	s_and_saveexec_b64 s[10:11], s[38:39]
	ds_write_b128 v177, v[116:119]
	s_or_b64 exec, exec, s[10:11]
	s_lshl_b32 s7, s22, 3
	s_lshl_b32 s6, s23, 8
	s_and_b32 s7, s7, 0xc0
	s_or_b32 s6, s7, s6
	s_add_u32 s6, s6, s20
	s_addc_u32 s7, 0, s21
	v_and_b32_e32 v0, 3, v182
	v_lshl_add_u64 v[124:125], s[6:7], 0, v[184:185]
	v_lshlrev_b32_e32 v0, 4, v0
	v_lshl_add_u64 v[124:125], v[124:125], 0, v[0:1]
	v_mul_u32_u24_e32 v228, 0x110, v183
	v_lshl_add_u64 v[182:183], s[16:17], 0, v[124:125]
	s_movk_i32 s20, 0x100
	s_waitcnt vmcnt(0)
	v_readfirstlane_b32 s100, v172
	v_readfirstlane_b32 s101, v173
	v_and_b32_e32 v0, 15, v186
	v_lshlrev_b32_e32 v0, 4, v0
	v_subrev_u32_e32 v2, s100, v2
	v_lshl_add_u32 v2, v168, 11, v2
	v_lshl_or_b32 v174, v174, 11, v0
	v_lshl_or_b32 v176, v176, 11, v0
	v_lshl_or_b32 v178, v178, 11, v0
	v_lshl_or_b32 v180, v180, 11, v0
	v_add_u32_e32 v0, v171, v228
	s_add_u32 s100, s100, 0x40000
	s_addc_u32 s101, s101, 0
	s_branch .LBB0_113

.LBB0_113:
	s_cmpk_lg_i32 s20, 0x1000
	s_cselect_b32 s7, 0x40000, 0
	s_add_u32 s100, s100, s7
	s_addc_u32 s101, s101, 0
	s_sub_u32 s6, s100, 0x1800
	s_subb_u32 s7, s101, 0
	s_waitcnt lgkmcnt(0)
	s_barrier
	ds_read_b128 v[140:143], v204
	ds_read_b128 v[144:147], v204 offset:64
	ds_read_b128 v[148:151], v205
	ds_read_b128 v[152:155], v205 offset:16
	ds_read_b128 v[156:159], v205 offset:32
	ds_read_b128 v[160:163], v205 offset:48
	global_load_dwordx4 v[124:127], v174, s[100:101]
	global_load_dwordx4 v[128:131], v176, s[100:101]
	global_load_dwordx4 v[132:135], v178, s[100:101]
	global_load_dwordx4 v[136:139], v180, s[100:101]
	s_and_saveexec_b64 s[10:11], s[38:39]
	s_cbranch_execz .LBB0_115
	global_load_dwordx4 v[116:119], v174, s[6:7]
.LBB0_115:
	s_or_b64 exec, exec, s[10:11]
	ds_read_u16 v238, v0
	ds_read_u16 v242, v0 offset:272
	ds_read_u16 v239, v0 offset:544
	ds_read_u16 v243, v0 offset:816
	ds_read_u16 v240, v0 offset:1088
	ds_read_u16 v244, v0 offset:1360
	ds_read_u16 v241, v0 offset:1632
	ds_read_u16 v245, v0 offset:1904
	s_waitcnt lgkmcnt(11)
	v_mfma_f32_16x16x32_bf16 v[140:143], v[4:7], v[148:151], v[140:143]
	s_waitcnt lgkmcnt(9)
	v_mfma_f32_16x16x32_bf16 v[144:147], v[12:15], v[156:159], v[144:147]
	v_mfma_f32_16x16x32_bf16 v[140:143], v[8:11], v[152:155], v[140:143]
	s_waitcnt lgkmcnt(8)
	v_mfma_f32_16x16x32_bf16 v[144:147], v[16:19], v[160:163], v[144:147]
	s_waitcnt lgkmcnt(4)
	v_perm_b32 v239, v243, v239, s8
	v_perm_b32 v238, v242, v238, s8
	s_waitcnt lgkmcnt(2)
	v_perm_b32 v240, v244, v240, s8
	s_waitcnt lgkmcnt(0)
	v_perm_b32 v241, v245, v241, s8
	s_cmp_eq_u64 s[38:39], 0
	s_cbranch_scc0 .Lrnn_w0
	s_waitcnt vmcnt(5)
	s_branch .Lrnn_wd

.Lrnn_wd:
	ds_write_b16 v175, v120
	ds_write_b16_d16_hi v175, v120 offset:272
	ds_write_b16 v175, v121 offset:544
	ds_write_b16_d16_hi v175, v121 offset:816
	ds_write_b16 v175, v122 offset:1088
	ds_write_b16_d16_hi v175, v122 offset:1360
	ds_write_b16 v175, v123 offset:1632
	ds_write_b16_d16_hi v175, v123 offset:1904
	s_nop 0
	global_load_dwordx4 v[120:123], v2, s[100:101]
	global_store_dwordx4 v[182:183], v[238:241], off
	v_cvt_pk_bf16_f32 v140, v140, v141
	v_cvt_pk_bf16_f32 v141, v142, v143
	v_cvt_pk_bf16_f32 v142, v144, v145
	v_cvt_pk_bf16_f32 v143, v146, v147
	v_cndmask_b32_e32 v184, 0, v142, vcc
	v_cndmask_b32_e32 v185, 0, v143, vcc
	v_mfma_f32_16x16x32_bf16 v[144:147], v[52:55], v[140:143], 0
	v_cndmask_b32_e32 v229, 0, v140, vcc
	v_cndmask_b32_e32 v230, 0, v141, vcc
	v_mfma_f32_16x16x32_bf16 v[148:151], v[68:71], v[140:143], 0
	v_mfma_f32_16x16x32_bf16 v[152:155], v[84:87], v[140:143], 0
	v_mfma_f32_16x16x32_bf16 v[156:159], v[100:103], v[140:143], 0
	ds_read_b128 v[140:143], v204 offset:128
	ds_read_b128 v[160:163], v205 offset:64
	ds_read_b128 v[164:167], v205 offset:80
	ds_read_b128 v[190:193], v204 offset:192
	ds_read_b128 v[238:241], v205 offset:96
	ds_read_b128 v[242:245], v205 offset:112
	s_waitcnt lgkmcnt(4)
	v_mfma_f32_16x16x32_bf16 v[140:143], v[20:23], v[160:163], v[140:143]
	s_waitcnt lgkmcnt(1)
	v_mfma_f32_16x16x32_bf16 v[160:163], v[28:31], v[238:241], v[190:193]
	v_mfma_f32_16x16x32_bf16 v[140:143], v[24:27], v[164:167], v[140:143]
	s_waitcnt lgkmcnt(0)
	v_mfma_f32_16x16x32_bf16 v[160:163], v[32:35], v[242:245], v[160:163]
	s_nop 5
	v_cvt_pk_bf16_f32 v140, v140, v141
	v_cvt_pk_bf16_f32 v141, v142, v143
	v_cvt_pk_bf16_f32 v142, v160, v161
	v_cvt_pk_bf16_f32 v143, v162, v163
	v_cndmask_b32_e64 v185, v185, v143, s[40:41]
	v_cndmask_b32_e64 v184, v184, v142, s[40:41]
	v_mfma_f32_16x16x32_bf16 v[144:147], v[56:59], v[140:143], v[144:147]
	v_cndmask_b32_e64 v230, v230, v141, s[40:41]
	v_cndmask_b32_e64 v229, v229, v140, s[40:41]
	v_mfma_f32_16x16x32_bf16 v[148:151], v[72:75], v[140:143], v[148:151]
	v_mfma_f32_16x16x32_bf16 v[152:155], v[88:91], v[140:143], v[152:155]
	v_mfma_f32_16x16x32_bf16 v[156:159], v[104:107], v[140:143], v[156:159]
	ds_read_b128 v[140:143], v204 offset:256
	ds_read_b128 v[160:163], v205 offset:128
	ds_read_b128 v[164:167], v205 offset:144
	ds_read_b128 v[190:193], v204 offset:320
	ds_read_b128 v[238:241], v205 offset:160
	ds_read_b128 v[242:245], v205 offset:176
	s_waitcnt lgkmcnt(4)
	v_mfma_f32_16x16x32_bf16 v[140:143], v[36:39], v[160:163], v[140:143]
	s_waitcnt lgkmcnt(1)
	v_mfma_f32_16x16x32_bf16 v[160:163], v[44:47], v[238:241], v[190:193]
	v_mfma_f32_16x16x32_bf16 v[140:143], v[40:43], v[164:167], v[140:143]
	s_waitcnt lgkmcnt(0)
	v_mfma_f32_16x16x32_bf16 v[160:163], v[48:51], v[242:245], v[160:163]
	s_nop 5
	v_cvt_pk_bf16_f32 v140, v140, v141
	v_cvt_pk_bf16_f32 v141, v142, v143
	v_cvt_pk_bf16_f32 v142, v160, v161
	v_cvt_pk_bf16_f32 v143, v162, v163
	v_cndmask_b32_e64 v231, v184, v142, s[42:43]
	v_cndmask_b32_e64 v184, v185, v143, s[42:43]
	v_mfma_f32_16x16x32_bf16 v[144:147], v[60:63], v[140:143], v[144:147]
	v_cndmask_b32_e64 v229, v229, v140, s[42:43]
	v_cndmask_b32_e64 v230, v230, v141, s[42:43]
	v_mfma_f32_16x16x32_bf16 v[148:151], v[76:79], v[140:143], v[148:151]
	v_mfma_f32_16x16x32_bf16 v[152:155], v[92:95], v[140:143], v[152:155]
	v_mfma_f32_16x16x32_bf16 v[160:163], v[108:111], v[140:143], v[156:159]
	ds_read_b128 v[140:143], v204 offset:384
	s_nop 1
	ds_read_b128 v[156:159], v205 offset:192
	ds_read_b128 v[164:167], v205 offset:208
	ds_read_b128 v[190:193], v204 offset:448
	ds_read_b128 v[238:241], v205 offset:224
	ds_read_b128 v[242:245], v205 offset:240
	ds_read_b128 v[246:249], v206
	s_waitcnt lgkmcnt(0)
	v_mfma_f32_16x16x32_bf16 v[140:143], v[246:249], v[156:159], v[140:143]
	ds_read_b128 v[156:159], v207
	s_waitcnt lgkmcnt(0)
	v_mfma_f32_16x16x32_bf16 v[156:159], v[156:159], v[238:241], v[190:193]
	s_nop 2
	ds_read_b128 v[190:193], v208
	s_waitcnt lgkmcnt(0)
	v_mfma_f32_16x16x32_bf16 v[140:143], v[190:193], v[164:167], v[140:143]
	ds_read_b128 v[164:167], v209
	s_waitcnt lgkmcnt(0)
	v_mfma_f32_16x16x32_bf16 v[156:159], v[164:167], v[242:245], v[156:159]
	s_nop 4
	v_cvt_pk_bf16_f32 v164, v140, v141
	v_cvt_pk_bf16_f32 v165, v142, v143
	s_nop 0
	v_cvt_pk_bf16_f32 v166, v156, v157
	v_cvt_pk_bf16_f32 v167, v158, v159
	v_cndmask_b32_e64 v184, v184, v167, s[44:45]
	v_cndmask_b32_e64 v185, v231, v166, s[44:45]
	v_mfma_f32_16x16x32_bf16 v[156:159], v[64:67], v[164:167], v[144:147]
	v_mfma_f32_16x16x32_bf16 v[144:147], v[80:83], v[164:167], v[148:151]
	v_mfma_f32_16x16x32_bf16 v[148:151], v[96:99], v[164:167], v[152:155]
	s_nop 2
	v_cndmask_b32_e64 v152, v230, v165, s[44:45]
	v_cndmask_b32_e64 v153, v229, v164, s[44:45]
	v_mfma_f32_16x16x32_bf16 v[140:143], v[112:115], v[164:167], v[160:163]
	v_lshlrev_b32_e32 v232, 16, v153
	v_and_b32_e32 v231, 0xffff0000, v153
	v_lshlrev_b32_e32 v230, 16, v152
	v_and_b32_e32 v229, 0xffff0000, v152
	v_lshlrev_b32_e32 v190, 16, v185
	v_and_b32_e32 v191, 0xffff0000, v185
	v_lshlrev_b32_e32 v192, 16, v184
	v_and_b32_e32 v193, 0xffff0000, v184
	ds_read_b128 v[160:163], v210
	ds_read_b128 v[152:155], v211
	ds_read_b128 v[164:167], v212
	ds_read_b128 v[238:241], v217
	ds_read_b128 v[242:245], v218
	ds_read_b128 v[246:249], v219
	s_waitcnt lgkmcnt(5)
	v_add_f32_e32 v156, v156, v160
	v_add_f32_e32 v157, v157, v161
	v_add_f32_e32 v158, v158, v162
	v_add_f32_e32 v159, v159, v163
	s_waitcnt lgkmcnt(4)
	v_add_f32_e32 v148, v148, v152
	v_add_f32_e32 v149, v149, v153
	v_add_f32_e32 v150, v150, v154
	v_add_f32_e32 v151, v151, v155
	v_exp_f32_e32 v156, v156
	v_exp_f32_e32 v157, v157
	v_exp_f32_e32 v158, v158
	v_exp_f32_e32 v159, v159
	v_exp_f32_e32 v148, v148
	v_exp_f32_e32 v149, v149
	v_exp_f32_e32 v150, v150
	v_exp_f32_e32 v151, v151
	s_waitcnt lgkmcnt(2)
	v_add_f32_e32 v144, v144, v238
	v_add_f32_e32 v145, v145, v239
	v_add_f32_e32 v146, v146, v240
	v_add_f32_e32 v147, v147, v241
	s_waitcnt lgkmcnt(1)
	v_add_f32_e32 v140, v140, v242
	v_add_f32_e32 v141, v141, v243
	v_add_f32_e32 v142, v142, v244
	v_add_f32_e32 v143, v143, v245
	v_exp_f32_e32 v144, v144
	v_exp_f32_e32 v145, v145
	v_exp_f32_e32 v146, v146
	v_exp_f32_e32 v147, v147
	v_exp_f32_e32 v140, v140
	v_exp_f32_e32 v141, v141
	v_exp_f32_e32 v142, v142
	v_exp_f32_e32 v143, v143
	v_add_f32_e32 v156, 1.0, v156
	v_add_f32_e32 v157, 1.0, v157
	v_add_f32_e32 v158, 1.0, v158
	v_add_f32_e32 v159, 1.0, v159
	v_add_f32_e32 v144, 1.0, v144
	v_add_f32_e32 v145, 1.0, v145
	v_add_f32_e32 v146, 1.0, v146
	v_add_f32_e32 v147, 1.0, v147
	v_add_f32_e32 v148, 1.0, v148
	v_add_f32_e32 v149, 1.0, v149
	v_add_f32_e32 v150, 1.0, v150
	v_add_f32_e32 v151, 1.0, v151
	v_add_f32_e32 v140, 1.0, v140
	v_add_f32_e32 v141, 1.0, v141
	v_add_f32_e32 v142, 1.0, v142
	v_add_f32_e32 v143, 1.0, v143
	v_rcp_f32_e64 v156, -v156
	v_rcp_f32_e64 v157, -v157
	v_rcp_f32_e64 v158, -v158
	v_rcp_f32_e64 v159, -v159
	v_rcp_f32_e64 v144, -v144
	v_rcp_f32_e64 v145, -v145
	v_rcp_f32_e64 v146, -v146
	v_rcp_f32_e64 v147, -v147
	v_rcp_f32_e32 v148, v148
	v_rcp_f32_e32 v149, v149
	v_rcp_f32_e32 v150, v150
	v_rcp_f32_e32 v151, v151
	v_rcp_f32_e32 v140, v140
	v_rcp_f32_e32 v141, v141
	v_rcp_f32_e32 v142, v142
	v_rcp_f32_e32 v143, v143
	s_waitcnt lgkmcnt(0)
	v_mul_f32_e32 v156, v164, v156
	v_mul_f32_e32 v157, v165, v157
	v_mul_f32_e32 v158, v166, v158
	v_mul_f32_e32 v159, v167, v159
	v_mul_f32_e32 v144, v246, v144
	v_mul_f32_e32 v145, v247, v145
	v_mul_f32_e32 v146, v248, v146
	v_mul_f32_e32 v147, v249, v147
	v_exp_f32_e32 v156, v156
	v_exp_f32_e32 v157, v157
	v_exp_f32_e32 v158, v158
	v_exp_f32_e32 v159, v159
	v_exp_f32_e32 v144, v144
	v_exp_f32_e32 v145, v145
	v_exp_f32_e32 v146, v146
	v_exp_f32_e32 v147, v147
	v_mul_f32_e32 v148, v148, v232
	v_mul_f32_e32 v149, v149, v231
	v_mul_f32_e32 v150, v150, v230
	v_mul_f32_e32 v151, v151, v229
	v_mul_f32_e32 v140, v140, v190
	v_mul_f32_e32 v141, v141, v191
	v_mul_f32_e32 v142, v142, v192
	v_mul_f32_e32 v143, v143, v193
	v_fma_f32 v160, -v156, v156, 1.0
	v_fma_f32 v161, -v157, v157, 1.0
	v_fma_f32 v162, -v158, v158, 1.0
	v_fma_f32 v163, -v159, v159, 1.0
	v_fma_f32 v238, -v144, v144, 1.0
	v_fma_f32 v239, -v145, v145, 1.0
	v_fma_f32 v240, -v146, v146, 1.0
	v_fma_f32 v241, -v147, v147, 1.0
	v_sqrt_f32_e32 v160, v160
	v_sqrt_f32_e32 v161, v161
	v_sqrt_f32_e32 v162, v162
	v_sqrt_f32_e32 v163, v163
	v_sqrt_f32_e32 v238, v238
	v_sqrt_f32_e32 v239, v239
	v_sqrt_f32_e32 v240, v240
	v_sqrt_f32_e32 v241, v241
	v_mul_f32_e32 v148, v148, v160
	v_mul_f32_e32 v149, v149, v161
	v_mul_f32_e32 v150, v150, v162
	v_mul_f32_e32 v151, v151, v163
	v_mul_f32_e32 v140, v140, v238
	v_mul_f32_e32 v141, v141, v239
	v_mul_f32_e32 v142, v142, v240
	v_mul_f32_e32 v143, v143, v241
	ds_write2_b32 v213, v156, v148 offset1:1
	ds_write2_b32 v214, v157, v149 offset1:1
	ds_write2_b32 v215, v158, v150 offset1:1
	ds_write2_b32 v216, v159, v151 offset1:1
	ds_write2_b32 v220, v144, v140 offset1:1
	ds_write2_b32 v221, v145, v141 offset1:1
	ds_write2_b32 v222, v146, v142 offset1:1
	ds_write2_b32 v223, v147, v143 offset1:1
	v_mov_b32_e32 v161, 0
	s_waitcnt lgkmcnt(0)
	s_barrier
	ds_read_b128 v[148:151], v224
	ds_read_b128 v[152:155], v224 offset:16
	ds_read_b128 v[144:147], v224 offset:32
	ds_read_b128 v[140:143], v224 offset:48
	s_waitcnt lgkmcnt(3)
	v_fma_f32 v149, 0, v148, v149
	v_fma_f32 v156, v150, v149, v151
	v_mul_f32_e32 v157, v148, v150
	s_waitcnt lgkmcnt(2)
	v_fma_f32 v158, v152, v156, v153
	v_mul_f32_e32 v159, v157, v152
	v_mul_f32_e32 v160, v154, v159
	v_fmac_f32_e32 v155, v154, v158
	s_waitcnt lgkmcnt(1)
	v_fma_f32 v145, v144, v155, v145
	v_mul_f32_e32 v144, v144, v160
	v_mul_f32_e32 v154, v146, v144
	v_fmac_f32_e32 v147, v146, v145
	s_waitcnt lgkmcnt(0)
	v_fma_f32 v141, v140, v147, v141
	v_mul_f32_e32 v140, v140, v154
	v_mul_f32_e32 v146, v142, v140
	v_fmac_f32_e32 v143, v142, v141
	v_mov_b32_e32 v150, v143
	v_mov_b32_e32 v142, v146
	v_mov_b32_e32 v151, 1.0
	v_fmac_f32_dpp v150, v150, v142 row_shr:1 row_mask:0xf bank_mask:0xf
	v_mul_f32_dpp v142, v142, v142 row_shr:1 row_mask:0xf bank_mask:0xf
	s_nop 0
	v_fmac_f32_dpp v150, v150, v142 row_shr:2 row_mask:0xf bank_mask:0xf
	v_mul_f32_dpp v142, v142, v142 row_shr:2 row_mask:0xf bank_mask:0xf
	s_nop 0
	v_fmac_f32_dpp v150, v150, v142 row_shr:4 row_mask:0xf bank_mask:0xf
	v_mul_f32_dpp v142, v142, v142 row_shr:4 row_mask:0xf bank_mask:0xf
	s_nop 0
	v_fmac_f32_dpp v150, v150, v142 row_shr:8 row_mask:0xf bank_mask:0xf
	v_mul_f32_dpp v142, v142, v142 row_shr:8 row_mask:0xf bank_mask:0xf
	s_nop 0
	v_mov_b32_dpp v161, v150 row_shr:1 row_mask:0xf bank_mask:0xf
	v_mov_b32_dpp v151, v142 row_shr:1 row_mask:0xf bank_mask:0xf
	v_fmac_f32_e32 v150, v142, v225
	v_fmac_f32_e32 v161, v151, v225
	ds_bpermute_b32 v225, v196, v150
	ds_read_b128 v[150:153], v226
	v_fmac_f32_e32 v145, v144, v161
	v_fmac_f32_e32 v149, v148, v161
	v_fmac_f32_e32 v147, v154, v161
	v_fmac_f32_e32 v141, v140, v161
	s_waitcnt lgkmcnt(0)
	v_lshlrev_b32_e32 v163, 16, v152
	v_lshlrev_b32_e32 v142, 16, v150
	v_mul_f32_e32 v144, v145, v163
	v_mul_f32_e32 v145, 0xbfb8aa3b, v163
	v_mul_f32_e32 v148, v149, v142
	v_mul_f32_e32 v142, 0xbfb8aa3b, v142
	v_exp_f32_e32 v145, v145
	v_exp_f32_e32 v142, v142
	v_and_b32_e32 v150, 0xffff0000, v150
	v_and_b32_e32 v152, 0xffff0000, v152
	v_add_f32_e32 v145, 1.0, v145
	v_add_f32_e32 v142, 1.0, v142
	v_rcp_f32_e32 v145, v145
	v_rcp_f32_e32 v142, v142
	v_lshlrev_b32_e32 v164, 16, v153
	v_lshlrev_b32_e32 v162, 16, v151
	v_fmac_f32_e32 v156, v157, v161
	v_mul_f32_e32 v149, 0xbfb8aa3b, v150
	v_mul_f32_e32 v144, v144, v145
	v_mul_f32_e32 v145, v147, v152
	v_mul_f32_e32 v147, 0xbfb8aa3b, v152
	v_mul_f32_e32 v140, v141, v164
	v_mul_f32_e32 v141, 0xbfb8aa3b, v164
	v_mul_f32_e32 v142, v148, v142
	v_mul_f32_e32 v148, v156, v150
	v_exp_f32_e32 v149, v149
	v_mul_f32_e32 v150, 0xbfb8aa3b, v162
	v_exp_f32_e32 v147, v147
	v_exp_f32_e32 v141, v141
	v_exp_f32_e32 v150, v150
	v_add_f32_e32 v149, 1.0, v149
	v_add_f32_e32 v147, 1.0, v147
	v_add_f32_e32 v141, 1.0, v141
	v_rcp_f32_e32 v149, v149
	v_add_f32_e32 v150, 1.0, v150
	v_rcp_f32_e32 v147, v147
	v_rcp_f32_e32 v141, v141
	v_rcp_f32_e32 v150, v150
	v_and_b32_e32 v153, 0xffff0000, v153
	v_fmac_f32_e32 v158, v159, v161
	v_and_b32_e32 v151, 0xffff0000, v151
	v_mul_f32_e32 v148, v148, v149
	v_mul_f32_e32 v149, v158, v162
	v_fmac_f32_e32 v155, v160, v161
	v_mul_f32_e32 v145, v145, v147
	v_mul_f32_e32 v147, v140, v141
	v_mul_f32_e32 v141, 0xbfb8aa3b, v153
	v_mul_f32_e32 v149, v149, v150
	v_mul_f32_e32 v150, v155, v151
	v_mul_f32_e32 v151, 0xbfb8aa3b, v151
	v_exp_f32_e32 v141, v141
	v_exp_f32_e32 v151, v151
	v_fmac_f32_e32 v143, v146, v161
	v_mul_f32_e32 v140, v143, v153
	v_add_f32_e32 v141, 1.0, v141
	v_add_f32_e32 v151, 1.0, v151
	v_rcp_f32_e32 v141, v141
	v_rcp_f32_e32 v151, v151
	v_mul_f32_e32 v143, v140, v141
	v_mul_f32_e32 v150, v150, v151
	v_cvt_pk_bf16_f32 v140, v142, v148
	v_cvt_pk_bf16_f32 v141, v149, v150
	v_cvt_pk_bf16_f32 v142, v144, v145
	v_cvt_pk_bf16_f32 v143, v147, v143
	ds_write_b128 v227, v[140:143]
	s_waitcnt vmcnt(5)
	ds_write_b128 v177, v[124:127] offset:816
	s_waitcnt vmcnt(4)
	ds_write_b128 v179, v[128:131] offset:816
	s_waitcnt vmcnt(3)
	ds_write_b128 v181, v[132:135] offset:816
	s_waitcnt vmcnt(2)
	ds_write_b128 v199, v[136:139] offset:816
	s_and_saveexec_b64 s[10:11], s[38:39]
	s_cbranch_execz .Lrnn_halo_done
	ds_write_b128 v177, v[116:119]

	.amdhsa_kernel _Z6mk_fwd4Args
		.amdhsa_group_segment_fixed_size 0
		.amdhsa_private_segment_fixed_size 0
		.amdhsa_kernarg_size 424
		.amdhsa_user_sgpr_count 2
		.amdhsa_user_sgpr_dispatch_ptr 0
		.amdhsa_user_sgpr_queue_ptr 0
		.amdhsa_user_sgpr_kernarg_segment_ptr 1
		.amdhsa_user_sgpr_dispatch_id 0
		.amdhsa_user_sgpr_kernarg_preload_length 0
		.amdhsa_user_sgpr_kernarg_preload_offset 0
		.amdhsa_user_sgpr_private_segment_size 0
		.amdhsa_uses_dynamic_stack 0
		.amdhsa_enable_private_segment 0
		.amdhsa_system_sgpr_workgroup_id_x 1
		.amdhsa_system_sgpr_workgroup_id_y 0
		.amdhsa_system_sgpr_workgroup_id_z 0
		.amdhsa_system_sgpr_workgroup_info 0
		.amdhsa_system_vgpr_workitem_id 2
		.amdhsa_next_free_vgpr 256
		.amdhsa_next_free_sgpr 102
		.amdhsa_accum_offset 256
		.amdhsa_reserve_vcc 1
		.amdhsa_float_round_mode_32 0
		.amdhsa_float_round_mode_16_64 0
		.amdhsa_float_denorm_mode_32 3
		.amdhsa_float_denorm_mode_16_64 3
		.amdhsa_dx10_clamp 1
		.amdhsa_ieee_mode 1
		.amdhsa_fp16_overflow 0
		.amdhsa_tg_split 0
		.amdhsa_exception_fp_ieee_invalid_op 0
		.amdhsa_exception_fp_denorm_src 0
		.amdhsa_exception_fp_ieee_div_zero 0
		.amdhsa_exception_fp_ieee_overflow 0
		.amdhsa_exception_fp_ieee_underflow 0
		.amdhsa_exception_fp_ieee_inexact 0
		.amdhsa_exception_int_div_zero 0
	.end_amdhsa_kernel

amdhsa.kernels:
  - .agpr_count:     0
    .args:
      - .offset:         0
        .size:           168
        .value_kind:     by_value
      - .offset:         168
        .size:           4
        .value_kind:     hidden_block_count_x
      - .offset:         172
        .size:           4
        .value_kind:     hidden_block_count_y
      - .offset:         176
        .size:           4
        .value_kind:     hidden_block_count_z
      - .offset:         180
        .size:           2
        .value_kind:     hidden_group_size_x
      - .offset:         182
        .size:           2
        .value_kind:     hidden_group_size_y
      - .offset:         184
        .size:           2
        .value_kind:     hidden_group_size_z
      - .offset:         186
        .size:           2
        .value_kind:     hidden_remainder_x
      - .offset:         188
        .size:           2
        .value_kind:     hidden_remainder_y
      - .offset:         190
        .size:           2
        .value_kind:     hidden_remainder_z
      - .offset:         208
        .size:           8
        .value_kind:     hidden_global_offset_x
      - .offset:         216
        .size:           8
        .value_kind:     hidden_global_offset_y
      - .offset:         224
        .size:           8
        .value_kind:     hidden_global_offset_z
      - .offset:         232
        .size:           2
        .value_kind:     hidden_grid_dims
      - .offset:         256
        .size:           8
        .value_kind:     hidden_multigrid_sync_arg
      - .offset:         288
        .size:           4
        .value_kind:     hidden_dynamic_lds_size
    .group_segment_fixed_size: 0
    .kernarg_segment_align: 8
    .kernarg_segment_size: 424
    .language:       OpenCL C
    .language_version:
      - 2
      - 0
    .max_flat_workgroup_size: 512
    .name:           _Z6mk_fwd4Args
    .private_segment_fixed_size: 0
    .sgpr_count:     108
    .sgpr_spill_count: 167
    .symbol:         _Z6mk_fwd4Args.kd
    .uniform_work_group_size: 1
    .uses_dynamic_stack: false
    .vgpr_count:     256
    .vgpr_spill_count: 0
    .wavefront_size: 64
